# X1 MLA row-op loop: issue the row's cq/ckv/k_rope/rope-table loads together at the iteration top (counted vmcnt) instead of 4 serialized round trips
# speedup vs baseline: 1.0021x; 1.0021x over previous
; DI unsigned f2bf(float f) { unsigned u = __builtin_bit_cast(unsigned, f); return (u + 0x7fffu + ((u >> 16) & 1u)) >> 16; }
; DI float bf1(bf16_t b) { return __uint_as_float(((unsigned)b) << 16); }
; DI void unpack8(const u32x4 w, float (&f)[8]) { f[0] = bflo(w.x); f[1] = bfhi(w.x); f[2] = bflo(w.y); f[3] = bfhi(w.y); f[4] = bflo(w.z); f[5] = bfhi(w.z); f[6] = bflo(w.w); f[7] = bfhi(w.w); }
; DI float shx(float v, int o, int lane) { return __int_as_float(__builtin_amdgcn_ds_bpermute((lane ^ o) << 2, __float_as_int(v))); }
; __global__ void __launch_bounds__(512, 2) fwd_mega(Args a_unused) {
;     ...
;             for (int row = gw; row < T_; row += NGW) {
;                 const bf16_t* zr = zb + (size_t)row * NZ;
;                 { float f[8]; float ss = 0.f; if (lane < 48) { unpack8(*(const u32x4*)(zr + ZCQ + 8 * lane), f);
;     ...
;                 { const float v = bf1(zr[ZKR + lane]); const float ot = shx(v, 32, lane); const f32x2 t = ((const f32x2*)(ws + WS_ROPE))[(size_t)row * 32 + (lane & 31)];
;                   const float res = lane < 32 ? v * t.x - ot * t.y : ot * t.y + v * t.x;
;                   ((bf16_t*)(ws + WS_KRB))[(size_t)row * 64 + lane] = (bf16_t)f2bf(res); }
.LBB0_430:
	s_or_b64 exec, exec, s[0:1]
	s_waitcnt lgkmcnt(0)
	v_readlane_b32 s0, v253, 60
	v_readlane_b32 s1, v253, 61
	s_add_i32 s4, s4, s80
	s_cmpk_gt_i32 s4, 0x7fff
	s_waitcnt vmcnt(1)
	v_lshlrev_b32_e32 v37, 16, v236
	ds_bpermute_b32 v38, v36, v37
	s_waitcnt lgkmcnt(0)
	v_mul_f32_e32 v15, v235, v38
	v_cndmask_b32_e64 v15, v15, -v15, s[8:9]
	v_fmac_f32_e32 v15, v234, v37
	v_bfe_u32 v14, v15, 16, 1
	v_add3_u32 v37, v15, v14, s33
	v_lshl_add_u64 v[14:15], s[44:45], 0, v[2:3]
	v_lshl_add_u64 v[2:3], v[2:3], 0, s[0:1]
	v_readlane_b32 s0, v253, 62
	v_readlane_b32 s1, v253, 63
	global_store_short_d16_hi v[14:15], v37, off
	s_nop 0
	v_lshl_add_u64 v[4:5], v[4:5], 0, s[0:1]
	v_readlane_b32 s0, v254, 0
	v_readlane_b32 s1, v254, 1
	s_nop 1
	v_lshl_add_u64 v[6:7], v[6:7], 0, s[0:1]
	v_readlane_b32 s0, v253, 50
	v_readlane_b32 s1, v253, 51
	s_nop 1
	v_lshl_add_u64 v[8:9], v[8:9], 0, s[0:1]
	v_readlane_b32 s0, v253, 52
	v_readlane_b32 s1, v253, 53
	s_nop 1
	v_lshl_add_u64 v[10:11], v[10:11], 0, s[0:1]
	v_lshl_add_u64 v[12:13], v[12:13], 0, s[0:1]
	s_cbranch_scc1 .LBB0_440
.LBB0_431:
	v_mov_b32_e32 v37, 0
	v_lshl_add_u64 v[14:15], s[44:45], 0, v[10:11]
	v_add_co_u32_e32 v16, vcc, 0x13c00000, v14
	s_nop 1
	v_addc_co_u32_e32 v17, vcc, 0, v15, vcc
	global_load_dwordx4 v[20:23], v[16:17], off offset:3088
	global_load_dwordx4 v[28:31], v[16:17], off offset:3856
	v_lshl_add_u64 v[232:233], s[44:45], 0, v[12:13]
	global_load_ushort v236, v[232:233], off
	v_lshl_add_u64 v[232:233], s[44:45], 0, v[4:5]
	global_load_dwordx2 v[234:235], v[232:233], off
	s_and_saveexec_b64 s[0:1], s[6:7]
	s_cbranch_execz .LBB0_433
	s_waitcnt vmcnt(3)
	v_lshlrev_b32_e32 v16, 16, v20
	v_and_b32_e32 v17, 0xffff0000, v20
	v_lshlrev_b32_e32 v18, 16, v21
	v_and_b32_e32 v19, 0xffff0000, v21
	v_pk_mul_f32 v[38:39], v[16:17], v[16:17]
	v_pk_mul_f32 v[40:41], v[18:19], v[18:19]
	v_add_f32_e32 v37, v38, v39
	v_lshlrev_b32_e32 v20, 16, v22
	v_and_b32_e32 v21, 0xffff0000, v22
	v_add_f32_e32 v37, v37, v40
	v_pk_mul_f32 v[42:43], v[20:21], v[20:21]
	v_add_f32_e32 v37, v37, v41
	v_lshlrev_b32_e32 v22, 16, v23
	v_and_b32_e32 v23, 0xffff0000, v23
	v_add_f32_e32 v37, v37, v42
	v_pk_mul_f32 v[44:45], v[22:23], v[22:23]
	v_add_f32_e32 v37, v37, v43
	v_add_f32_e32 v37, v37, v44
	v_add_f32_e32 v37, v37, v45

; DI void unpack8(const u32x4 w, float (&f)[8]) { f[0] = bflo(w.x); f[1] = bfhi(w.x); f[2] = bflo(w.y); f[3] = bfhi(w.y); f[4] = bflo(w.z); f[5] = bfhi(w.z); f[6] = bflo(w.w); f[7] = bfhi(w.w); }
; __global__ void __launch_bounds__(512, 2) fwd_mega(Args a_unused) {
;     ...
;                 { float f[8]; float ss = 0.f; if (lane < 32) { unpack8(*(const u32x4*)(zr + ZCKV + 8 * lane), f);
; #pragma unroll
;                         for (int e = 0; e < 8; ++e) ss += f[e] * f[e]; }
.LBB0_435:
	s_or_b64 exec, exec, s[0:1]
	s_nop 0
	v_mov_b32_e32 v38, 0
	s_and_saveexec_b64 s[0:1], s[8:9]
	s_cbranch_execz .LBB0_437
	s_waitcnt vmcnt(1)
	v_lshlrev_b32_e32 v24, 16, v28
	v_and_b32_e32 v25, 0xffff0000, v28
	v_lshlrev_b32_e32 v26, 16, v29
	v_and_b32_e32 v27, 0xffff0000, v29
	v_pk_mul_f32 v[14:15], v[24:25], v[24:25]
	s_waitcnt lgkmcnt(0)
	v_pk_mul_f32 v[38:39], v[26:27], v[26:27]
	v_add_f32_e32 v14, v14, v15
	v_lshlrev_b32_e32 v28, 16, v30
	v_and_b32_e32 v29, 0xffff0000, v30
	v_add_f32_e32 v14, v14, v38
	v_pk_mul_f32 v[40:41], v[28:29], v[28:29]
	v_add_f32_e32 v14, v14, v39
	v_lshlrev_b32_e32 v30, 16, v31
	v_and_b32_e32 v31, 0xffff0000, v31
	v_add_f32_e32 v14, v14, v40
	v_pk_mul_f32 v[42:43], v[30:31], v[30:31]
	v_add_f32_e32 v14, v14, v41
	v_add_f32_e32 v14, v14, v42
	v_add_f32_e32 v38, v14, v43
